# cross-attention: static s_setprio 1 for the younger wave half (waves 4-7), reset at phase exit
# baseline (speedup 1.0000x reference)
; __device__ __forceinline__ void cross_attn_phase(const Params& p, int layer, char* shm, int wv) {
;   const u16* caq = p.B0; u16* cao = p.B1;
;   const u16* mK = p.memK + (long)layer * NB * MEML * DM; const u16* mVT = p.memVT + (long)layer * NB * DM * MEML;
;   u32x4 ckreg[4], cvreg[4];
;   for (int i = blockIdx.x; i < 1024; i += gridDim.x) {
.LBB0_2081:
	s_cmp_lt_u32 s97, 0x100
	s_cbranch_scc1 .Lxa_noprio
	s_setprio 1

; __device__ __forceinline__ void xcd_barrier(const XcdBarrier& b, bool t0) {
;     asm volatile("s_waitcnt vmcnt(0)" ::: "memory");
;     __syncthreads();
;     if (t0) {
;         unsigned* bar = b.bar;
;         __builtin_amdgcn_s_waitcnt(0);
;         unsigned nloc = b.st[0], nx = b.st[1];
;         if (nloc == 0u) { xcd_barrier_complete(bar, b.x, nloc, nx); b.st[0] = nloc; b.st[1] = nx; }
.LBB0_2087:
	s_setprio 0
	s_mov_b64 s[6:7], s[54:55]
	s_mov_b32 s0, -1
	s_getreg_b32 s8, hwreg(HW_REG_XCC_ID, 0, 4)
	s_nop 0
	v_mbcnt_lo_u32_b32 v0, s0, 0
	v_mbcnt_hi_u32_b32 v0, s0, v0
	v_or_b32_e32 v0, s97, v0
	s_waitcnt vmcnt(0)
	s_nop 0
	v_cmp_eq_u32_e32 vcc, 0, v0
	s_barrier
	s_and_saveexec_b64 s[0:1], vcc
	s_cbranch_execz .LBB0_2139
	v_readlane_b32 s9, v254, 32
	s_load_dwordx2 s[10:11], s[54:55], 0x80
	v_mov_b32_e32 v0, s9
	ds_read_b32 v2, v0
	ds_read_b32 v3, v0 offset:8
	s_waitcnt lgkmcnt(0)
	v_readfirstlane_b32 s12, v3
	v_readfirstlane_b32 s13, v2
	s_cmp_eq_u32 s12, 2
	s_cbranch_scc1 .Lxl3_full
	s_cmp_eq_u32 s13, 0
	s_cbranch_scc1 .Lxl3_full
	s_cmp_eq_u32 s12, 1
	s_cbranch_scc1 .Lxl3_go
	v_mov_b32_e32 v4, 0x1fa02000
	global_load_dwordx4 v[8:11], v4, s[10:11] sc1
	global_load_dwordx4 v[12:15], v4, s[10:11] offset:16 sc1
	global_load_dwordx4 v[16:19], v4, s[10:11] offset:32 sc1
	global_load_dwordx4 v[20:23], v4, s[10:11] offset:48 sc1
	s_lshr_b32 s16, s70, 3
	s_xor_b32 s17, s70, 0x100
	v_mov_b32_e32 v5, s17
	s_waitcnt vmcnt(0)
	v_mul_lo_u32 v6, v8, v8
	v_mul_lo_u32 v7, v9, s16
	v_sub_u32_e32 v6, v7, v6
	v_or_b32_e32 v5, v5, v6
	v_mul_lo_u32 v6, v10, v10
	v_mul_lo_u32 v7, v11, s16
	v_sub_u32_e32 v6, v7, v6
	v_or_b32_e32 v5, v5, v6
	v_mul_lo_u32 v6, v12, v12
	v_mul_lo_u32 v7, v13, s16
	v_sub_u32_e32 v6, v7, v6
	v_or_b32_e32 v5, v5, v6
	v_mul_lo_u32 v6, v14, v14
	v_mul_lo_u32 v7, v15, s16
	v_sub_u32_e32 v6, v7, v6
	v_or_b32_e32 v5, v5, v6
	v_mul_lo_u32 v6, v16, v16
	v_mul_lo_u32 v7, v17, s16
	v_sub_u32_e32 v6, v7, v6
	v_or_b32_e32 v5, v5, v6
	v_mul_lo_u32 v6, v18, v18
	v_mul_lo_u32 v7, v19, s16
	v_sub_u32_e32 v6, v7, v6
	v_or_b32_e32 v5, v5, v6
	v_mul_lo_u32 v6, v20, v20
	v_mul_lo_u32 v7, v21, s16
	v_sub_u32_e32 v6, v7, v6
	v_or_b32_e32 v5, v5, v6
	v_mul_lo_u32 v6, v22, v22
	v_mul_lo_u32 v7, v23, s16
	v_sub_u32_e32 v6, v7, v6
	v_or_b32_e32 v5, v5, v6
	s_nop 0
	v_readfirstlane_b32 s17, v5
	s_nop 3
	s_cmp_eq_u32 s17, 0
	s_cselect_b32 s12, 1, 2
	v_mov_b32_e32 v3, s12
	ds_write_b32 v0, v3 offset:8
	s_waitcnt lgkmcnt(0)
	s_cmp_eq_u32 s12, 1
	s_cbranch_scc0 .Lxl3_full
